# v16 + diff loop: K tiles staged one tile further ahead so the next tile's first-half K/Q fragments are read before the barrier
# speedup vs baseline: 1.0174x; 1.0007x over previous
.Ldq_prio_1:
	global_load_dwordx4 v[226:229], v[188:189], off
	v_add_u32_e32 v14, v204, v197
	v_add_u32_e32 v15, v204, v198
	ds_read_b128 v[2:5], v14
	ds_read_b128 v[6:9], v14 offset:4096
	ds_read_b128 v[10:13], v209
	ds_read_b128 v[242:245], v15
	ds_read_b128 v[246:249], v15 offset:4096
	ds_read_b128 v[210:213], v209 offset:1024
	s_waitcnt lgkmcnt(3)
	v_mfma_f32_32x32x16_bf16 v[128:143], v[2:5], v[10:13], 0
	v_mfma_f32_32x32x16_bf16 v[112:127], v[6:9], v[10:13], 0
	s_waitcnt lgkmcnt(0)
	v_mfma_f32_32x32x16_bf16 v[128:143], v[242:245], v[210:213], v[128:143]
	v_mfma_f32_32x32x16_bf16 v[112:127], v[246:249], v[210:213], v[112:127]
	v_add_u32_e32 v14, v204, v199
	v_add_u32_e32 v15, v204, v200
	ds_read_b128 v[2:5], v14
	ds_read_b128 v[6:9], v14 offset:4096
	ds_read_b128 v[10:13], v209 offset:2048
	ds_read_b128 v[242:245], v15
	ds_read_b128 v[246:249], v15 offset:4096
	ds_read_b128 v[210:213], v209 offset:3072
	s_waitcnt lgkmcnt(3)
	v_mfma_f32_32x32x16_bf16 v[128:143], v[2:5], v[10:13], v[128:143]
	v_mfma_f32_32x32x16_bf16 v[112:127], v[6:9], v[10:13], v[112:127]
	s_waitcnt lgkmcnt(0)
	v_mfma_f32_32x32x16_bf16 v[128:143], v[242:245], v[210:213], v[128:143]
	v_mfma_f32_32x32x16_bf16 v[112:127], v[246:249], v[210:213], v[112:127]
	s_add_i32 s14, s26, 0xffffff60
	s_cmp_gt_u32 s14, 0xfffffea0
	s_cbranch_scc1 .Ldq_near_2
	s_sub_i32 s14, s26, 31
	s_cmpk_gt_i32 s14, 0x80
	s_cselect_b32 s14, 0x408, 0
	s_add_i32 s14, s18, s14
	v_mov_b32_e32 v1, s14
	ds_read_b32 v14, v1 offset:29312
	s_nop 7
	s_waitcnt lgkmcnt(0)
	s_nop 3
	v_max3_f32 v225, v128, v129, v130
	v_max3_f32 v225, v225, v131, v132
	v_max3_f32 v225, v225, v133, v134
	v_max3_f32 v225, v225, v135, v136
	v_max3_f32 v225, v225, v137, v138
	v_max3_f32 v225, v225, v139, v140
	v_max3_f32 v225, v225, v141, v142
	v_max3_f32 v225, v225, v143, v112
	v_max3_f32 v225, v225, v113, v114
	v_max3_f32 v225, v225, v115, v116
	v_max3_f32 v225, v225, v117, v118
	v_max3_f32 v225, v225, v119, v120
	v_max3_f32 v225, v225, v121, v122
	v_max3_f32 v225, v225, v123, v124
	v_max3_f32 v225, v225, v125, v126
	v_max_f32_e32 v225, v225, v127
	v_fma_f32 v225, v225, s2, v14
	v_mov_b32_e32 v2, v225
	v_mov_b32_e32 v3, v225
	s_nop 1
	v_permlane32_swap_b32 v2, v3
	s_nop 1
	s_nop 0
	v_max3_f32 v225, v225, v2, v3
	v_add_f32_e32 v2, 0x41000000, v208
	v_cmp_gt_f32_e32 vcc, v225, v2
	s_cbranch_vccz .Ldq_norescale_4
	v_max_f32_e32 v2, v225, v225
	v_max_f32_e32 v3, v208, v208
	v_max_f32_e32 v2, v3, v2
	v_sub_f32_e32 v3, v208, v2
	v_exp_f32_e32 v3, v3
	v_mov_b32_e32 v208, v2
	s_nop 0
	v_mul_f32_e32 v187, v187, v3
	v_mov_b32_e32 v214, v3
	s_mov_b32 s100, 1

.Ldq_smdone_3:
	s_nop 0
	v_cvt_pk_bf16_f32 v80, v128, v129
	v_cvt_pk_bf16_f32 v81, v130, v131
	v_cvt_pk_bf16_f32 v82, v132, v133
	v_cvt_pk_bf16_f32 v83, v134, v135
	v_cvt_pk_bf16_f32 v84, v136, v137
	v_cvt_pk_bf16_f32 v85, v138, v139
	v_cvt_pk_bf16_f32 v86, v140, v141
	v_cvt_pk_bf16_f32 v87, v142, v143
	v_cvt_pk_bf16_f32 v88, v112, v113
	v_cvt_pk_bf16_f32 v89, v114, v115
	v_cvt_pk_bf16_f32 v90, v116, v117
	v_cvt_pk_bf16_f32 v91, v118, v119
	v_cvt_pk_bf16_f32 v92, v120, v121
	v_cvt_pk_bf16_f32 v93, v122, v123
	v_cvt_pk_bf16_f32 v94, v124, v125
	v_cvt_pk_bf16_f32 v95, v126, v127
	v_add_f32_e32 v112, v112, v114
	v_add_f32_e32 v113, v113, v115
	v_add_f32_e32 v116, v116, v118
	v_add_f32_e32 v117, v117, v119
	v_add_f32_e32 v120, v120, v122
	v_add_f32_e32 v121, v121, v123
	v_add_f32_e32 v124, v124, v126
	v_add_f32_e32 v125, v125, v127
	v_add_f32_e32 v128, v128, v130
	v_add_f32_e32 v129, v129, v131
	v_add_f32_e32 v132, v132, v134
	v_add_f32_e32 v133, v133, v135
	v_add_f32_e32 v136, v136, v138
	v_add_f32_e32 v137, v137, v139
	v_add_f32_e32 v140, v140, v142
	v_add_f32_e32 v141, v141, v143
	v_add_f32_e32 v112, v112, v116
	v_add_f32_e32 v113, v113, v117
	v_add_f32_e32 v120, v120, v124
	v_add_f32_e32 v121, v121, v125
	v_add_f32_e32 v128, v128, v132
	v_add_f32_e32 v129, v129, v133
	v_add_f32_e32 v136, v136, v140
	v_add_f32_e32 v137, v137, v141
	v_add_f32_e32 v112, v112, v120
	v_add_f32_e32 v113, v113, v121
	v_add_f32_e32 v128, v128, v136
	v_add_f32_e32 v129, v129, v137
	v_add_f32_e32 v112, v112, v128
	v_add_f32_e32 v113, v113, v129
	v_add_f32_e32 v112, v112, v113
	v_add_f32_e32 v187, v187, v112
	s_mov_b32 s100, 0
	s_mov_b32 s25, 1
	s_add_i32 s26, s26, 64
	s_waitcnt vmcnt(3)
	v_add_u32_e32 v251, 0x4000, v192
	ds_write_b128 v251, v[156:159]
	s_mov_b64 s[14:15], 0x180000
	v_lshl_add_u64 v[188:189], v[188:189], 0, s[14:15]
	s_waitcnt vmcnt(0)
	v_mov_b32_e32 v156, v226
	v_mov_b32_e32 v157, v227
	v_mov_b32_e32 v158, v228
	v_mov_b32_e32 v159, v229
	s_waitcnt lgkmcnt(0)
	s_barrier
	v_lshl_add_u32 v1, s25, 13, v204
	v_add_u32_e32 v14, v1, v197
	v_add_u32_e32 v15, v1, v198
	ds_read_b128 v[2:5], v14
	ds_read_b128 v[6:9], v14 offset:4096
	ds_read_b128 v[10:13], v209
	ds_read_b128 v[242:245], v15
	ds_read_b128 v[246:249], v15 offset:4096
	ds_read_b128 v[210:213], v209 offset:1024
.Ldq_top_6:
	s_bitcmp1_b32 s27, 0
	s_cselect_b32 s14, 0x5000, 0
	v_add_u32_e32 v250, s14, v201
	ds_read_b64_tr_b16 v[96:97], v250 offset:24576
	ds_read_b64_tr_b16 v[100:101], v250 offset:24640
	ds_read_b64_tr_b16 v[104:105], v250 offset:24704
	ds_read_b64_tr_b16 v[108:109], v250 offset:24768
	ds_read_b64_tr_b16 v[98:99], v250 offset:27136
	ds_read_b64_tr_b16 v[102:103], v250 offset:27200
	ds_read_b64_tr_b16 v[106:107], v250 offset:27264
	ds_read_b64_tr_b16 v[110:111], v250 offset:27328
	s_waitcnt lgkmcnt(11)
	v_mfma_f32_32x32x16_bf16 v[128:143], v[2:5], v[10:13], 0
	v_mfma_f32_32x32x16_bf16 v[112:127], v[6:9], v[10:13], 0
	s_waitcnt lgkmcnt(8)
	v_mfma_f32_32x32x16_bf16 v[128:143], v[242:245], v[210:213], v[128:143]
	v_mfma_f32_32x32x16_bf16 v[112:127], v[246:249], v[210:213], v[112:127]
	v_lshl_add_u32 v1, s25, 13, v204
	v_add_u32_e32 v14, v1, v199
	v_add_u32_e32 v15, v1, v200
	ds_read_b128 v[2:5], v14
	ds_read_b128 v[6:9], v14 offset:4096
	ds_read_b128 v[10:13], v209 offset:2048
	ds_read_b128 v[242:245], v15
	ds_read_b128 v[246:249], v15 offset:4096
	ds_read_b128 v[210:213], v209 offset:3072
	s_add_i32 s14, s27, 1
	s_bitcmp1_b32 s14, 0
	s_cselect_b32 s15, 0x5000, 0
	s_waitcnt vmcnt(0)
	v_add3_u32 v251, s15, v193, v194
	ds_write_b128 v251, v[148:151] offset:24576
	v_add3_u32 v251, s15, v195, v196
	ds_write_b128 v251, v[152:155] offset:24576
	s_cmp_gt_u32 s27, 28
	s_cbranch_scc1 .Ldq_skipkw_7
	s_add_i32 s14, s25, 2
	s_sub_i32 s15, s14, 3
	s_cmp_gt_u32 s14, 2
	s_cselect_b32 s14, s15, s14
	v_lshl_add_u32 v251, s14, 13, v192
	ds_write_b128 v251, v[156:159]
.Ldq_skipkw_7:
	s_cmp_gt_u32 s27, 27
	s_cbranch_scc1 .Ldq_skipk_8
	v_lshl_add_u64 v[14:15], v[188:189], 0, s[4:5]
	global_load_dwordx4 v[156:159], v[14:15], off
.Ldq_skipk_8:
	v_lshl_add_u64 v[14:15], v[184:185], 0, s[4:5]
	global_load_dwordx4 v[148:151], v[14:15], off
	v_lshl_add_u64 v[14:15], v[182:183], 0, s[4:5]
	global_load_dwordx4 v[152:155], v[14:15], off
	s_waitcnt lgkmcnt(5)
	v_mfma_f32_32x32x16_bf16 v[128:143], v[2:5], v[10:13], v[128:143]
	v_mfma_f32_32x32x16_bf16 v[112:127], v[6:9], v[10:13], v[112:127]
	s_waitcnt lgkmcnt(2)
	v_mfma_f32_32x32x16_bf16 v[128:143], v[242:245], v[210:213], v[128:143]
	v_mfma_f32_32x32x16_bf16 v[112:127], v[246:249], v[210:213], v[112:127]
	s_add_i32 s14, s26, 0xffffff60
	s_cmp_gt_u32 s14, 0xfffffea0
	s_cbranch_scc1 .Ldq_near_9
	s_sub_i32 s14, s26, 31
	s_cmpk_gt_i32 s14, 0x80
	s_cselect_b32 s14, 0x408, 0
	s_add_i32 s14, s18, s14
	v_mov_b32_e32 v1, s14
	ds_read_b32 v14, v1 offset:29312
	ds_read_b64_tr_b16 v[226:227], v250 offset:29696
	ds_read_b64_tr_b16 v[230:231], v250 offset:29760
	ds_read_b64_tr_b16 v[234:235], v250 offset:29824
	ds_read_b64_tr_b16 v[238:239], v250 offset:29888
	ds_read_b64_tr_b16 v[228:229], v250 offset:32256
	ds_read_b64_tr_b16 v[232:233], v250 offset:32320
	ds_read_b64_tr_b16 v[236:237], v250 offset:32384
	ds_read_b64_tr_b16 v[240:241], v250 offset:32448
	s_waitcnt lgkmcnt(8)
	s_nop 3
	v_mfma_f32_32x32x16_bf16 v[64:79], v[96:99], v[80:83], v[64:79]
	v_max3_f32 v225, v128, v129, v130
	v_max3_f32 v225, v225, v131, v132
	v_max3_f32 v225, v225, v133, v134
	v_max3_f32 v225, v225, v135, v136
	v_mfma_f32_32x32x16_bf16 v[48:63], v[100:103], v[80:83], v[48:63]
	v_max3_f32 v225, v225, v137, v138
	v_max3_f32 v225, v225, v139, v140
	v_max3_f32 v225, v225, v141, v142
	v_max3_f32 v225, v225, v143, v112
	v_mfma_f32_32x32x16_bf16 v[32:47], v[104:107], v[80:83], v[32:47]
	v_max3_f32 v225, v225, v113, v114
	v_max3_f32 v225, v225, v115, v116
	v_max3_f32 v225, v225, v117, v118
	v_max3_f32 v225, v225, v119, v120
	v_mfma_f32_32x32x16_bf16 v[16:31], v[108:111], v[80:83], v[16:31]
	v_max3_f32 v225, v225, v121, v122
	v_max3_f32 v225, v225, v123, v124
	v_max3_f32 v225, v225, v125, v126
	v_max_f32_e32 v225, v225, v127
	ds_read_b64_tr_b16 v[96:97], v250 offset:34816
	ds_read_b64_tr_b16 v[100:101], v250 offset:34880
	ds_read_b64_tr_b16 v[104:105], v250 offset:34944
	ds_read_b64_tr_b16 v[108:109], v250 offset:35008
	ds_read_b64_tr_b16 v[98:99], v250 offset:37376
	ds_read_b64_tr_b16 v[102:103], v250 offset:37440
	ds_read_b64_tr_b16 v[106:107], v250 offset:37504
	ds_read_b64_tr_b16 v[110:111], v250 offset:37568
	v_fma_f32 v225, v225, s2, v14
	v_mov_b32_e32 v2, v225
	v_mov_b32_e32 v3, v225
	s_nop 1
	v_permlane32_swap_b32 v2, v3
	s_nop 1
	s_nop 0
	v_max3_f32 v225, v225, v2, v3
	v_add_f32_e32 v2, 0x41000000, v208
	v_cmp_gt_f32_e32 vcc, v225, v2
	s_cbranch_vccz .Ldq_norescale_11
	v_max_f32_e32 v2, v225, v225
	v_max_f32_e32 v3, v208, v208
	v_max_f32_e32 v2, v3, v2
	v_sub_f32_e32 v3, v208, v2
	v_exp_f32_e32 v3, v3
	v_mov_b32_e32 v208, v2
	s_nop 0
	v_mul_f32_e32 v187, v187, v3
	v_mov_b32_e32 v214, v3
	s_mov_b32 s100, 1

.Ldq_noapply_13:
	s_add_i32 s14, s25, 1
	s_cmp_lg_u32 s25, 2
	s_cselect_b32 s14, s14, 0
	v_lshl_add_u32 v1, s14, 13, v204
	v_add_u32_e32 v14, v1, v197
	v_add_u32_e32 v15, v1, v198
	ds_read_b128 v[2:5], v14
	ds_read_b128 v[6:9], v14 offset:4096
	ds_read_b128 v[10:13], v209
	ds_read_b128 v[242:245], v15
	ds_read_b128 v[246:249], v15 offset:4096
	ds_read_b128 v[210:213], v209 offset:1024
	s_waitcnt lgkmcnt(6)
	s_barrier
	s_add_i32 s14, s25, 1
	s_cmp_lg_u32 s25, 2
	s_cselect_b32 s25, s14, 0
	s_add_u32 s4, s4, 0x180000
	s_addc_u32 s5, s5, 0
	s_add_i32 s26, s26, 64
	s_add_i32 s27, s27, 1
	s_cmp_lt_u32 s27, 30
	s_cbranch_scc1 .Ldq_top_6
	s_bitcmp1_b32 s27, 0
	s_cselect_b32 s14, 0x5000, 0
	v_add_u32_e32 v250, s14, v201
	ds_read_b64_tr_b16 v[96:97], v250 offset:24576
	ds_read_b64_tr_b16 v[100:101], v250 offset:24640
	ds_read_b64_tr_b16 v[104:105], v250 offset:24704
	ds_read_b64_tr_b16 v[108:109], v250 offset:24768
	ds_read_b64_tr_b16 v[98:99], v250 offset:27136
	ds_read_b64_tr_b16 v[102:103], v250 offset:27200
	ds_read_b64_tr_b16 v[106:107], v250 offset:27264
	ds_read_b64_tr_b16 v[110:111], v250 offset:27328
	s_waitcnt lgkmcnt(11)
	v_mfma_f32_32x32x16_bf16 v[128:143], v[2:5], v[10:13], 0
	v_mfma_f32_32x32x16_bf16 v[112:127], v[6:9], v[10:13], 0
	s_waitcnt lgkmcnt(8)
	v_mfma_f32_32x32x16_bf16 v[128:143], v[242:245], v[210:213], v[128:143]
	v_mfma_f32_32x32x16_bf16 v[112:127], v[246:249], v[210:213], v[112:127]
	v_lshl_add_u32 v1, s25, 13, v204
	v_add_u32_e32 v14, v1, v199
	v_add_u32_e32 v15, v1, v200
	ds_read_b128 v[2:5], v14
	ds_read_b128 v[6:9], v14 offset:4096
	ds_read_b128 v[10:13], v209 offset:2048
	ds_read_b128 v[242:245], v15
	ds_read_b128 v[246:249], v15 offset:4096
	ds_read_b128 v[210:213], v209 offset:3072
	s_add_i32 s14, s27, 1
	s_bitcmp1_b32 s14, 0
	s_cselect_b32 s15, 0x5000, 0
	s_waitcnt vmcnt(0)
	v_add3_u32 v251, s15, v193, v194
	ds_write_b128 v251, v[148:151] offset:24576
	v_add3_u32 v251, s15, v195, v196
	ds_write_b128 v251, v[152:155] offset:24576
	s_waitcnt lgkmcnt(5)
	v_mfma_f32_32x32x16_bf16 v[128:143], v[2:5], v[10:13], v[128:143]
	v_mfma_f32_32x32x16_bf16 v[112:127], v[6:9], v[10:13], v[112:127]
	s_waitcnt lgkmcnt(2)
	v_mfma_f32_32x32x16_bf16 v[128:143], v[242:245], v[210:213], v[128:143]
	v_mfma_f32_32x32x16_bf16 v[112:127], v[246:249], v[210:213], v[112:127]
	s_add_i32 s14, s26, 0xffffff60
	s_cmp_gt_u32 s14, 0xfffffea0
	s_cbranch_scc1 .Ldq_near_14
	s_sub_i32 s14, s26, 31
	s_cmpk_gt_i32 s14, 0x80
	s_cselect_b32 s14, 0x408, 0
	s_add_i32 s14, s18, s14
	v_mov_b32_e32 v1, s14
	ds_read_b32 v14, v1 offset:29312
	ds_read_b64_tr_b16 v[226:227], v250 offset:29696
	ds_read_b64_tr_b16 v[230:231], v250 offset:29760
	ds_read_b64_tr_b16 v[234:235], v250 offset:29824
	ds_read_b64_tr_b16 v[238:239], v250 offset:29888
	ds_read_b64_tr_b16 v[228:229], v250 offset:32256
	ds_read_b64_tr_b16 v[232:233], v250 offset:32320
	ds_read_b64_tr_b16 v[236:237], v250 offset:32384
	ds_read_b64_tr_b16 v[240:241], v250 offset:32448
	s_waitcnt lgkmcnt(8)
	s_nop 3
	v_mfma_f32_32x32x16_bf16 v[64:79], v[96:99], v[80:83], v[64:79]
	v_max3_f32 v225, v128, v129, v130
	v_max3_f32 v225, v225, v131, v132
	v_max3_f32 v225, v225, v133, v134
	v_max3_f32 v225, v225, v135, v136
	v_mfma_f32_32x32x16_bf16 v[48:63], v[100:103], v[80:83], v[48:63]
	v_max3_f32 v225, v225, v137, v138
	v_max3_f32 v225, v225, v139, v140
	v_max3_f32 v225, v225, v141, v142
	v_max3_f32 v225, v225, v143, v112
	v_mfma_f32_32x32x16_bf16 v[32:47], v[104:107], v[80:83], v[32:47]
	v_max3_f32 v225, v225, v113, v114
	v_max3_f32 v225, v225, v115, v116
	v_max3_f32 v225, v225, v117, v118
	v_max3_f32 v225, v225, v119, v120
	v_mfma_f32_32x32x16_bf16 v[16:31], v[108:111], v[80:83], v[16:31]
	v_max3_f32 v225, v225, v121, v122
	v_max3_f32 v225, v225, v123, v124
	v_max3_f32 v225, v225, v125, v126
	v_max_f32_e32 v225, v225, v127
	ds_read_b64_tr_b16 v[96:97], v250 offset:34816
	ds_read_b64_tr_b16 v[100:101], v250 offset:34880
	ds_read_b64_tr_b16 v[104:105], v250 offset:34944
	ds_read_b64_tr_b16 v[108:109], v250 offset:35008
	ds_read_b64_tr_b16 v[98:99], v250 offset:37376
	ds_read_b64_tr_b16 v[102:103], v250 offset:37440
	ds_read_b64_tr_b16 v[106:107], v250 offset:37504
	ds_read_b64_tr_b16 v[110:111], v250 offset:37568
	v_fma_f32 v225, v225, s2, v14
	v_mov_b32_e32 v2, v225
	v_mov_b32_e32 v3, v225
	s_nop 1
	v_permlane32_swap_b32 v2, v3
	s_nop 1
	s_nop 0
	v_max3_f32 v225, v225, v2, v3
	v_add_f32_e32 v2, 0x41000000, v208
	v_cmp_gt_f32_e32 vcc, v225, v2
	s_cbranch_vccz .Ldq_norescale_16
	v_max_f32_e32 v2, v225, v225
	v_max_f32_e32 v3, v208, v208
	v_max_f32_e32 v2, v3, v2
	v_sub_f32_e32 v3, v208, v2
	v_exp_f32_e32 v3, v3
	v_mov_b32_e32 v208, v2
	s_nop 0
	v_mul_f32_e32 v187, v187, v3
	v_mov_b32_e32 v214, v3
	s_mov_b32 s100, 1
